# grid barrier: non-leader workgroups poll the cross-XCC release word directly instead of the per-XCC forwarded word (on top of win1 config)
# baseline (speedup 1.0000x reference)
.LBB0_78:
	s_or_b64 exec, exec, s[10:11]
	v_cvt_f32_u32_e32 v5, v3
	s_waitcnt vmcnt(0)
	v_readfirstlane_b32 s8, v4
	v_sub_u32_e32 v4, 0, v3
	v_rcp_iflag_f32_e32 v5, v5
	v_add_u32_e32 v6, s8, v2
	v_mul_f32_e32 v5, 0x4f7ffffe, v5
	v_cvt_u32_f32_e32 v5, v5
	v_mul_lo_u32 v2, v4, v5
	v_mul_hi_u32 v2, v5, v2
	v_add_u32_e32 v2, v5, v2
	v_mul_hi_u32 v2, v6, v2
	v_mul_lo_u32 v4, v2, v3
	v_sub_u32_e32 v4, v6, v4
	v_add_u32_e32 v5, 1, v2
	v_cmp_ge_u32_e32 vcc, v4, v3
	s_nop 1
	v_cndmask_b32_e32 v2, v2, v5, vcc
	v_sub_u32_e32 v5, v4, v3
	v_cndmask_b32_e32 v4, v4, v5, vcc
	v_add_u32_e32 v5, 1, v2
	v_cmp_ge_u32_e32 vcc, v4, v3
	v_add_u32_e32 v4, 1, v6
	s_nop 0
	v_cndmask_b32_e32 v2, v2, v5, vcc
	v_mul_lo_u32 v5, v3, v2
	v_add_u32_e32 v3, v5, v3
	v_cmp_ne_u32_e32 vcc, v4, v3
	s_and_saveexec_b64 s[8:9], vcc
	s_xor_b64 s[8:9], exec, s[8:9]
	s_cbranch_execz .LBB0_92
	s_waitcnt lgkmcnt(0)
	v_mov_b32_e32 v1, 0x3500
	global_load_dword v1, v1, s[4:5] sc1
	s_add_u32 s14, s4, 0x3500
	s_addc_u32 s15, s5, 0
	s_waitcnt vmcnt(0)
	v_cmp_eq_u32_e32 vcc, v1, v2
	s_and_saveexec_b64 s[10:11], vcc
	s_cbranch_execz .LBB0_91
	s_mov_b32 s12, 1
	s_mov_b64 s[26:27], 0
	v_mov_b32_e32 v1, 0
	s_branch .LBB0_82

.LBB0_335:
	s_or_b64 exec, exec, s[14:15]
	v_cvt_f32_u32_e32 v5, v3
	s_waitcnt vmcnt(0)
	v_readfirstlane_b32 s3, v4
	v_sub_u32_e32 v4, 0, v3
	v_rcp_iflag_f32_e32 v5, v5
	v_add_u32_e32 v6, s3, v2
	v_mul_f32_e32 v5, 0x4f7ffffe, v5
	v_cvt_u32_f32_e32 v5, v5
	v_mul_lo_u32 v2, v4, v5
	v_mul_hi_u32 v2, v5, v2
	v_add_u32_e32 v2, v5, v2
	v_mul_hi_u32 v2, v6, v2
	v_mul_lo_u32 v4, v2, v3
	v_sub_u32_e32 v4, v6, v4
	v_add_u32_e32 v5, 1, v2
	v_cmp_ge_u32_e32 vcc, v4, v3
	s_nop 1
	v_cndmask_b32_e32 v2, v2, v5, vcc
	v_sub_u32_e32 v5, v4, v3
	v_cndmask_b32_e32 v4, v4, v5, vcc
	v_add_u32_e32 v5, 1, v2
	v_cmp_ge_u32_e32 vcc, v4, v3
	v_add_u32_e32 v4, 1, v6
	s_nop 0
	v_cndmask_b32_e32 v2, v2, v5, vcc
	v_mul_lo_u32 v5, v3, v2
	v_add_u32_e32 v3, v5, v3
	v_cmp_ne_u32_e32 vcc, v4, v3
	s_and_saveexec_b64 s[4:5], vcc
	s_xor_b64 s[10:11], exec, s[4:5]
	s_cbranch_execz .LBB0_349
	s_waitcnt lgkmcnt(0)
	v_mov_b32_e32 v1, 0x3500
	global_load_dword v1, v1, s[6:7] sc1
	s_add_u32 s26, s6, 0x3500
	s_addc_u32 s27, s7, 0
	s_waitcnt vmcnt(0)
	v_cmp_eq_u32_e32 vcc, v1, v2
	s_and_saveexec_b64 s[14:15], vcc
	s_cbranch_execz .LBB0_348
	s_mov_b32 s4, 1
	s_mov_b64 s[44:45], 0
	v_mov_b32_e32 v1, 0
	s_branch .LBB0_339

.LBB0_455:
	s_or_b64 exec, exec, s[14:15]
	v_cvt_f32_u32_e32 v5, v3
	s_waitcnt vmcnt(0)
	v_readfirstlane_b32 s3, v4
	v_sub_u32_e32 v4, 0, v3
	v_rcp_iflag_f32_e32 v5, v5
	v_add_u32_e32 v6, s3, v2
	v_mul_f32_e32 v5, 0x4f7ffffe, v5
	v_cvt_u32_f32_e32 v5, v5
	v_mul_lo_u32 v2, v4, v5
	v_mul_hi_u32 v2, v5, v2
	v_add_u32_e32 v2, v5, v2
	v_mul_hi_u32 v2, v6, v2
	v_mul_lo_u32 v4, v2, v3
	v_sub_u32_e32 v4, v6, v4
	v_add_u32_e32 v5, 1, v2
	v_cmp_ge_u32_e32 vcc, v4, v3
	s_nop 1
	v_cndmask_b32_e32 v2, v2, v5, vcc
	v_sub_u32_e32 v5, v4, v3
	v_cndmask_b32_e32 v4, v4, v5, vcc
	v_add_u32_e32 v5, 1, v2
	v_cmp_ge_u32_e32 vcc, v4, v3
	v_add_u32_e32 v4, 1, v6
	s_nop 0
	v_cndmask_b32_e32 v2, v2, v5, vcc
	v_mul_lo_u32 v5, v3, v2
	v_add_u32_e32 v3, v5, v3
	v_cmp_ne_u32_e32 vcc, v4, v3
	s_and_saveexec_b64 s[4:5], vcc
	s_xor_b64 s[10:11], exec, s[4:5]
	s_cbranch_execz .LBB0_469
	s_waitcnt lgkmcnt(0)
	v_mov_b32_e32 v1, 0x3500
	global_load_dword v1, v1, s[6:7] sc1
	s_add_u32 s52, s6, 0x3500
	s_addc_u32 s53, s7, 0
	s_waitcnt vmcnt(0)
	v_cmp_eq_u32_e32 vcc, v1, v2
	s_and_saveexec_b64 s[14:15], vcc
	s_cbranch_execz .LBB0_468
	s_mov_b32 s4, 1
	s_mov_b64 s[68:69], 0
	v_mov_b32_e32 v1, 0
	s_branch .LBB0_459

.LBB0_721:
	s_or_b64 exec, exec, s[16:17]
	v_cvt_f32_u32_e32 v5, v3
	s_waitcnt vmcnt(0)
	v_readfirstlane_b32 s3, v4
	v_sub_u32_e32 v4, 0, v3
	v_rcp_iflag_f32_e32 v5, v5
	v_add_u32_e32 v6, s3, v2
	v_mul_f32_e32 v5, 0x4f7ffffe, v5
	v_cvt_u32_f32_e32 v5, v5
	v_mul_lo_u32 v2, v4, v5
	v_mul_hi_u32 v2, v5, v2
	v_add_u32_e32 v2, v5, v2
	v_mul_hi_u32 v2, v6, v2
	v_mul_lo_u32 v4, v2, v3
	v_sub_u32_e32 v4, v6, v4
	v_add_u32_e32 v5, 1, v2
	v_cmp_ge_u32_e32 vcc, v4, v3
	s_nop 1
	v_cndmask_b32_e32 v2, v2, v5, vcc
	v_sub_u32_e32 v5, v4, v3
	v_cndmask_b32_e32 v4, v4, v5, vcc
	v_add_u32_e32 v5, 1, v2
	v_cmp_ge_u32_e32 vcc, v4, v3
	v_add_u32_e32 v4, 1, v6
	s_nop 0
	v_cndmask_b32_e32 v2, v2, v5, vcc
	v_mul_lo_u32 v5, v3, v2
	v_add_u32_e32 v3, v5, v3
	v_cmp_ne_u32_e32 vcc, v4, v3
	s_and_saveexec_b64 s[4:5], vcc
	s_xor_b64 s[10:11], exec, s[4:5]
	s_cbranch_execz .LBB0_735
	s_waitcnt lgkmcnt(0)
	v_mov_b32_e32 v1, 0x3500
	global_load_dword v1, v1, s[6:7] sc1
	s_add_u32 s20, s6, 0x3500
	s_addc_u32 s21, s7, 0
	s_waitcnt vmcnt(0)
	v_cmp_eq_u32_e32 vcc, v1, v2
	s_and_saveexec_b64 s[16:17], vcc
	s_cbranch_execz .LBB0_734
	s_mov_b32 s4, 1
	s_mov_b64 s[52:53], 0
	v_mov_b32_e32 v1, 0
	s_branch .LBB0_725

.LBB0_942:
	s_or_b64 exec, exec, s[20:21]
	v_cvt_f32_u32_e32 v5, v3
	s_waitcnt vmcnt(0)
	v_readfirstlane_b32 s3, v4
	v_sub_u32_e32 v4, 0, v3
	v_rcp_iflag_f32_e32 v5, v5
	v_add_u32_e32 v6, s3, v2
	v_mul_f32_e32 v5, 0x4f7ffffe, v5
	v_cvt_u32_f32_e32 v5, v5
	v_mul_lo_u32 v2, v4, v5
	v_mul_hi_u32 v2, v5, v2
	v_add_u32_e32 v2, v5, v2
	v_mul_hi_u32 v2, v6, v2
	v_mul_lo_u32 v4, v2, v3
	v_sub_u32_e32 v4, v6, v4
	v_add_u32_e32 v5, 1, v2
	v_cmp_ge_u32_e32 vcc, v4, v3
	s_nop 1
	v_cndmask_b32_e32 v2, v2, v5, vcc
	v_sub_u32_e32 v5, v4, v3
	v_cndmask_b32_e32 v4, v4, v5, vcc
	v_add_u32_e32 v5, 1, v2
	v_cmp_ge_u32_e32 vcc, v4, v3
	v_add_u32_e32 v4, 1, v6
	s_nop 0
	v_cndmask_b32_e32 v2, v2, v5, vcc
	v_mul_lo_u32 v5, v3, v2
	v_add_u32_e32 v3, v5, v3
	v_cmp_ne_u32_e32 vcc, v4, v3
	s_and_saveexec_b64 s[4:5], vcc
	s_xor_b64 s[10:11], exec, s[4:5]
	s_cbranch_execz .LBB0_956
	s_waitcnt lgkmcnt(0)
	v_mov_b32_e32 v1, 0x3500
	global_load_dword v1, v1, s[6:7] sc1
	s_add_u32 s28, s6, 0x3500
	s_addc_u32 s29, s7, 0
	s_waitcnt vmcnt(0)
	v_cmp_eq_u32_e32 vcc, v1, v2
	s_and_saveexec_b64 s[20:21], vcc
	s_cbranch_execz .LBB0_955
	s_mov_b32 s4, 1
	s_mov_b64 s[52:53], 0
	v_mov_b32_e32 v1, 0
	s_branch .LBB0_946

.LBB0_1120:
	s_or_b64 exec, exec, s[10:11]
	v_cvt_f32_u32_e32 v5, v3
	s_waitcnt vmcnt(0)
	v_readfirstlane_b32 s3, v4
	v_sub_u32_e32 v4, 0, v3
	v_rcp_iflag_f32_e32 v5, v5
	v_add_u32_e32 v6, s3, v2
	v_mul_f32_e32 v5, 0x4f7ffffe, v5
	v_cvt_u32_f32_e32 v5, v5
	v_mul_lo_u32 v2, v4, v5
	v_mul_hi_u32 v2, v5, v2
	v_add_u32_e32 v2, v5, v2
	v_mul_hi_u32 v2, v6, v2
	v_mul_lo_u32 v4, v2, v3
	v_sub_u32_e32 v4, v6, v4
	v_add_u32_e32 v5, 1, v2
	v_cmp_ge_u32_e32 vcc, v4, v3
	s_nop 1
	v_cndmask_b32_e32 v2, v2, v5, vcc
	v_sub_u32_e32 v5, v4, v3
	v_cndmask_b32_e32 v4, v4, v5, vcc
	v_add_u32_e32 v5, 1, v2
	v_cmp_ge_u32_e32 vcc, v4, v3
	v_add_u32_e32 v4, 1, v6
	s_nop 0
	v_cndmask_b32_e32 v2, v2, v5, vcc
	v_mul_lo_u32 v5, v3, v2
	v_add_u32_e32 v3, v5, v3
	v_cmp_ne_u32_e32 vcc, v4, v3
	s_and_saveexec_b64 s[8:9], vcc
	s_xor_b64 s[8:9], exec, s[8:9]
	s_cbranch_execz .LBB0_1134
	s_waitcnt lgkmcnt(0)
	v_mov_b32_e32 v1, 0x3500
	global_load_dword v1, v1, s[4:5] sc1
	s_add_u32 s20, s4, 0x3500
	s_addc_u32 s21, s5, 0
	s_waitcnt vmcnt(0)
	v_cmp_eq_u32_e32 vcc, v1, v2
	s_and_saveexec_b64 s[10:11], vcc
	s_cbranch_execz .LBB0_1133
	s_mov_b32 s12, 1
	s_mov_b64 s[28:29], 0
	v_mov_b32_e32 v1, 0
	s_branch .LBB0_1124

.LBB0_1240:
	s_or_b64 exec, exec, s[10:11]
	v_cvt_f32_u32_e32 v5, v3
	s_waitcnt vmcnt(0)
	v_readfirstlane_b32 s3, v4
	v_sub_u32_e32 v4, 0, v3
	v_rcp_iflag_f32_e32 v5, v5
	v_add_u32_e32 v6, s3, v2
	v_mul_f32_e32 v5, 0x4f7ffffe, v5
	v_cvt_u32_f32_e32 v5, v5
	v_mul_lo_u32 v2, v4, v5
	v_mul_hi_u32 v2, v5, v2
	v_add_u32_e32 v2, v5, v2
	v_mul_hi_u32 v2, v6, v2
	v_mul_lo_u32 v4, v2, v3
	v_sub_u32_e32 v4, v6, v4
	v_add_u32_e32 v5, 1, v2
	v_cmp_ge_u32_e32 vcc, v4, v3
	s_nop 1
	v_cndmask_b32_e32 v2, v2, v5, vcc
	v_sub_u32_e32 v5, v4, v3
	v_cndmask_b32_e32 v4, v4, v5, vcc
	v_add_u32_e32 v5, 1, v2
	v_cmp_ge_u32_e32 vcc, v4, v3
	v_add_u32_e32 v4, 1, v6
	s_nop 0
	v_cndmask_b32_e32 v2, v2, v5, vcc
	v_mul_lo_u32 v5, v3, v2
	v_add_u32_e32 v3, v5, v3
	v_cmp_ne_u32_e32 vcc, v4, v3
	s_and_saveexec_b64 s[8:9], vcc
	s_xor_b64 s[8:9], exec, s[8:9]
	s_cbranch_execz .LBB0_1254
	s_waitcnt lgkmcnt(0)
	v_mov_b32_e32 v1, 0x3500
	global_load_dword v1, v1, s[4:5] sc1
	s_add_u32 s20, s4, 0x3500
	s_addc_u32 s21, s5, 0
	s_waitcnt vmcnt(0)
	v_cmp_eq_u32_e32 vcc, v1, v2
	s_and_saveexec_b64 s[10:11], vcc
	s_cbranch_execz .LBB0_1253
	s_mov_b32 s12, 1
	s_mov_b64 s[22:23], 0
	v_mov_b32_e32 v1, 0
	s_branch .LBB0_1244

.LBB0_1342:
	s_or_b64 exec, exec, s[10:11]
	v_cvt_f32_u32_e32 v5, v3
	s_waitcnt vmcnt(0)
	v_readfirstlane_b32 s3, v4
	v_sub_u32_e32 v4, 0, v3
	v_rcp_iflag_f32_e32 v5, v5
	v_add_u32_e32 v6, s3, v2
	v_mul_f32_e32 v5, 0x4f7ffffe, v5
	v_cvt_u32_f32_e32 v5, v5
	v_mul_lo_u32 v2, v4, v5
	v_mul_hi_u32 v2, v5, v2
	v_add_u32_e32 v2, v5, v2
	v_mul_hi_u32 v2, v6, v2
	v_mul_lo_u32 v4, v2, v3
	v_sub_u32_e32 v4, v6, v4
	v_add_u32_e32 v5, 1, v2
	v_cmp_ge_u32_e32 vcc, v4, v3
	s_nop 1
	v_cndmask_b32_e32 v2, v2, v5, vcc
	v_sub_u32_e32 v5, v4, v3
	v_cndmask_b32_e32 v4, v4, v5, vcc
	v_add_u32_e32 v5, 1, v2
	v_cmp_ge_u32_e32 vcc, v4, v3
	v_add_u32_e32 v4, 1, v6
	s_nop 0
	v_cndmask_b32_e32 v2, v2, v5, vcc
	v_mul_lo_u32 v5, v3, v2
	v_add_u32_e32 v3, v5, v3
	v_cmp_ne_u32_e32 vcc, v4, v3
	s_and_saveexec_b64 s[8:9], vcc
	s_xor_b64 s[8:9], exec, s[8:9]
	s_cbranch_execz .LBB0_1356
	s_waitcnt lgkmcnt(0)
	v_mov_b32_e32 v1, 0x3500
	global_load_dword v1, v1, s[4:5] sc1
	s_add_u32 s20, s4, 0x3500
	s_addc_u32 s21, s5, 0
	s_waitcnt vmcnt(0)
	v_cmp_eq_u32_e32 vcc, v1, v2
	s_and_saveexec_b64 s[10:11], vcc
	s_cbranch_execz .LBB0_1355
	s_mov_b32 s3, 1
	s_mov_b64 s[22:23], 0
	v_mov_b32_e32 v1, 0
	s_branch .LBB0_1346

.LBB0_1665:
	s_or_b64 exec, exec, s[6:7]
	v_cvt_f32_u32_e32 v5, v3
	s_waitcnt vmcnt(0)
	v_readfirstlane_b32 s4, v4
	v_sub_u32_e32 v4, 0, v3
	v_rcp_iflag_f32_e32 v5, v5
	v_add_u32_e32 v6, s4, v2
	v_mul_f32_e32 v5, 0x4f7ffffe, v5
	v_cvt_u32_f32_e32 v5, v5
	v_mul_lo_u32 v2, v4, v5
	v_mul_hi_u32 v2, v5, v2
	v_add_u32_e32 v2, v5, v2
	v_mul_hi_u32 v2, v6, v2
	v_mul_lo_u32 v4, v2, v3
	v_sub_u32_e32 v4, v6, v4
	v_add_u32_e32 v5, 1, v2
	v_cmp_ge_u32_e32 vcc, v4, v3
	s_nop 1
	v_cndmask_b32_e32 v2, v2, v5, vcc
	v_sub_u32_e32 v5, v4, v3
	v_cndmask_b32_e32 v4, v4, v5, vcc
	v_add_u32_e32 v5, 1, v2
	v_cmp_ge_u32_e32 vcc, v4, v3
	v_add_u32_e32 v4, 1, v6
	s_nop 0
	v_cndmask_b32_e32 v2, v2, v5, vcc
	v_mul_lo_u32 v5, v3, v2
	v_add_u32_e32 v3, v5, v3
	v_cmp_ne_u32_e32 vcc, v4, v3
	s_and_saveexec_b64 s[4:5], vcc
	s_xor_b64 s[4:5], exec, s[4:5]
	s_cbranch_execz .LBB0_1679
	s_waitcnt lgkmcnt(0)
	v_mov_b32_e32 v1, 0x3500
	global_load_dword v1, v1, s[64:65] sc1
	s_add_u32 s8, s64, 0x3500
	s_addc_u32 s9, s65, 0
	s_waitcnt vmcnt(0)
	v_cmp_eq_u32_e32 vcc, v1, v2
	s_and_saveexec_b64 s[6:7], vcc
	s_cbranch_execz .LBB0_1678
	s_mov_b32 s19, 1
	s_mov_b64 s[10:11], 0
	v_mov_b32_e32 v1, 0
	s_branch .LBB0_1669
